# dense attention item loop shifted +48 bytes (loop-head offset 44 mod 64), complementary pad after the phase
# baseline (speedup 1.0000x reference)
; DI int fresh_lane() { int l; asm volatile("v_mbcnt_lo_u32_b32 %0, -1, 0\n\tv_mbcnt_hi_u32_b32 %0, -1, %0" : "=v"(l)); return l; }
; #define FRESH_IDS() int tid_ = wave_s * 64 + fresh_lane(); asm volatile("" : "+v"(tid_)); const int tid = tid_, lane = tid & 63, wave = wave_s; (void)tid; (void)lane; (void)wave
; __global__ void __launch_bounds__(512, 2) fwd_kernel(Params p) {
;     ...
;     for (int rep_ = 0; rep_ < REP_ATTNC; ++rep_) { FRESH_IDS();
;         const int G_ = (int)gridDim.x, vcu = (G_ % 8 == 0) ? ((int)blockIdx.x & 7) * (G_ >> 3) + ((int)blockIdx.x >> 3) : (int)blockIdx.x;
;         for (int item = vcu; item < 1024; item += G_) {
;             const int qb = item & 15, head = (item >> 4) & 7, b = item >> 7, kvh = head >> 2;
;             int tl = wave * 64 + fresh_lane(); asm volatile("" : "+v"(tl));
;             const size_t qrow = (size_t)NCTX + (size_t)b * SEQ + qb * 256;
;             __syncthreads();
.LBB0_1525:
	s_or_b64 exec, exec, s[0:1]
	s_and_b32 s1, s75, 7
	s_ashr_i32 s2, s30, 3
	s_mul_i32 s1, s2, s1
	s_ashr_i32 s2, s75, 3
	s_and_b32 s0, s30, 7
	s_add_i32 s1, s1, s2
	s_cmp_eq_u32 s0, 0
	s_waitcnt lgkmcnt(0)
	s_barrier
	v_mbcnt_lo_u32_b32 v0, -1, 0
	v_mbcnt_hi_u32_b32 v0, -1, v0
	s_cselect_b32 s2, s1, s75
	s_mov_b32 s56, 0
	v_add_u32_e32 v0, s74, v0
	s_cmpk_gt_i32 s2, 0x3ff
	s_cbranch_scc1 .LBB0_1547
	s_add_u32 s3, s28, 0x1e500000
	s_addc_u32 s11, s29, 0
	s_add_u32 s0, s28, 0x1e512000
	s_addc_u32 s1, s29, 0
	v_mov_b32_e32 v177, 0
	s_mov_b32 s14, 0x42b504f3
	s_mov_b32 s10, 0x3e0293ee
	v_mov_b32_e32 v180, 0xf149f2ca
	s_mov_b64 s[12:13], 0x8000
	v_mov_b32_e32 v181, 0x110000
	s_nop 0
	s_nop 0
	s_nop 0
	s_nop 0
	s_nop 0
	s_nop 0
	s_nop 0
	s_nop 0
	s_nop 0
	s_nop 0
	s_nop 0
	s_nop 0
	s_branch .LBB0_1528

; DI void xcd_barrier(const XcdBarrier& b, int tid) {
;     asm volatile("s_waitcnt vmcnt(0)" ::: "memory");
;     __syncthreads();
;     if (tid == 0) {
;         unsigned* bar = b.bar;
;         __builtin_amdgcn_s_waitcnt(0);
;         unsigned nloc = b.st[0], nx = b.st[1];
;         if (nloc == 0u) { xcd_barrier_complete(bar, b.x, nloc, nx); b.st[0] = nloc; b.st[1] = nx; }
.LBB0_1547:
	s_nop 0
	s_nop 0
	s_nop 0
	s_nop 0
	v_mbcnt_lo_u32_b32 v0, -1, 0
	v_mbcnt_hi_u32_b32 v0, -1, v0
	s_nop 0
	v_add_u32_e32 v0, s74, v0
	s_waitcnt vmcnt(0)
	s_waitcnt vmcnt(63) expcnt(7) lgkmcnt(15)
	v_cmp_eq_u32_e32 vcc, 0, v0
	s_barrier
	s_and_saveexec_b64 s[0:1], vcc
	v_readlane_b32 s59, v254, 12
	s_cbranch_execz .LBB0_1599
	s_add_i32 s2, 0, 0x23ff0
	v_mov_b32_e32 v0, s2
	s_waitcnt vmcnt(0) expcnt(0) lgkmcnt(0)
	ds_read_b32 v2, v0
	s_add_i32 s2, 0, 0x23ff4
	v_mov_b32_e32 v0, s2
	ds_read_b32 v0, v0
	s_waitcnt lgkmcnt(1)
	v_cmp_ne_u32_e32 vcc, 0, v2
	s_cbranch_vccnz .LBB0_1563
	s_mov_b32 s2, 1
	v_mov_b32_e32 v16, 0
	s_branch .LBB0_1551
